# sample-attention tasks moved to blocks 128-255 (balance merged mixers phase); fused epilogue: X stores before sibling wait, no L1 invalidate
# speedup vs baseline: 1.1142x; 1.0150x over previous
; #define INP(i) ((const float*)ld_ptr(pb, (i)))
; __device__ __forceinline__ void attn_sample_wave(float* wl  , const bf16_t* Q, const bf16_t* Kb, const bf16_t* Vb, const float* ck, const float* cv, bf16_t* MIX, const float* sinks, int task, int lane) {
;     const int g = task & 3, kvh = (task >> 2) & 1, b = task >> 3, head = kvh * 4 + g;
;     float* qs = wl; float* ps = wl + 256;
; #pragma unroll
;     for (int t = 0; t < 4; ++t) qs[t * 64 + lane] = bf2f(Q[(size_t)(MP + b * 4 + t) * 512 + head * 64 + lane]);
;     asm volatile("s_waitcnt lgkmcnt(0)" ::: "memory");
;     float sc[3][4];
; #pragma unroll
;     for (int slot = 0; slot < 3; ++slot) {
;         const int j = slot * 64 + lane; const bool have = (slot < 2) || (lane < 4);
;         float d0 = 0.f, d1 = 0.f, d2 = 0.f, d3 = 0.f;
;         if (have) {
;             if (slot < 2) { const float* kr = ck + ((size_t)b * 128 + j) * 128 + kvh * 64;
; #pragma unroll 8
;                 for (int d4 = 0; d4 < 16; ++d4) { const f32x4 kv = *(const f32x4*)(kr + 4 * d4);
; #pragma unroll
;                     for (int i = 0; i < 4; ++i) { const int d = 4 * d4 + i; d0 += kv[i] * qs[d]; d1 += kv[i] * qs[64 + d]; d2 += kv[i] * qs[128 + d]; d3 += kv[i] * qs[192 + d]; } }
;             } else { const bf16_t* kr = Kb + (size_t)(MP + b * 4 + lane) * 128 + kvh * 64;
; #pragma unroll 16
;                 for (int d = 0; d < 64; ++d) { const float kv = bf2f(kr[d]); d0 += kv * qs[d]; d1 += kv * qs[64 + d]; d2 += kv * qs[128 + d]; d3 += kv * qs[192 + d]; } }
;         }
;         const float dd[4] = {d0, d1, d2, d3};
; #pragma unroll
;         for (int t = 0; t < 4; ++t) { const bool ok = have && ((slot < 2) ? (j > t) : (lane <= t)); sc[slot][t] = ok ? dd[t] : -1e30f; }
;     }
;     const float sink = sinks[head];
; __global__ void __launch_bounds__(512, 2) hybrid_fwd(Params P) {
;     ...
;                 const float* sinks = INP(14) + l * 8;
;                 for (int i = bid - 64; i < 128; i += G - 64) { const int task = 256 + i; MIX_TASK(task); }
.LBB0_1033:
	s_andn2_b64 vcc, exec, s[0:1]
	s_cbranch_vccnz .LBB0_1133
	v_readlane_b32 s0, v253, 0
	s_mov_b32 s2, s0
	v_readlane_b32 s0, v253, 1
	v_mbcnt_lo_u32_b32 v92, -1, 0
	v_mbcnt_hi_u32_b32 v92, -1, v92
	v_readlane_b32 s1, v253, 2
	s_cmp_gt_i32 s2, 63
	v_writelane_b32 v254, s0, 1
	v_readlane_b32 s0, v253, 7
	v_writelane_b32 v253, s1, 62
	v_lshl_add_u32 v134, s1, 6, v92
	v_mov_b32_e32 v101, s0
	ds_read_b64 v[0:1], v101 offset:280
	s_waitcnt lgkmcnt(0)
	v_readfirstlane_b32 s1, v1
	v_readfirstlane_b32 s0, v0
	s_nop 1
	v_writelane_b32 v253, s0, 63
	v_writelane_b32 v253, s2, 41
	s_nop 0
	v_writelane_b32 v254, s1, 0
	s_mov_b64 s[0:1], -1
	s_cbranch_scc0 .LBB0_1070
	ds_read_b64 v[0:1], v101 offset:112
	v_readlane_b32 s0, v253, 41
	s_cmpk_lt_u32 s0, 0x80
	s_waitcnt lgkmcnt(0)
	v_readfirstlane_b32 s0, v1
	v_readfirstlane_b32 s1, v0
	s_cbranch_scc1 .LBB0_1069
	s_lshl_b32 s74, s96, 3
	s_lshl_b64 s[2:3], s[74:75], 2
	s_add_u32 s12, s1, s2
	s_addc_u32 s13, s0, s3
	v_readlane_b32 s0, v253, 41
	v_readlane_b32 s10, v253, 62
	s_sub_i32 s20, s0, 128
	s_lshl_b32 s0, s10, 12
	s_add_i32 s21, s0, 0
	v_readlane_b32 s8, v253, 63
	v_readlane_b32 s9, v254, 0
	s_add_u32 s0, s8, 0x10200000
	s_addc_u32 s1, s9, 0
	s_add_u32 s22, s8, 0x11300000
	s_addc_u32 s23, s9, 0
	s_add_u32 s26, s8, 0x11800000
	s_addc_u32 s27, s9, 0
	s_add_u32 s2, s8, 0xe100000
	s_addc_u32 s3, s9, 0
	s_and_b32 s6, s10, 7
	s_lshl_b32 s7, s6, 7
	v_ashrrev_i32_e32 v93, 31, v92
	s_add_u32 s4, s0, s7
	s_addc_u32 s5, s1, 0
	v_lshlrev_b64 v[0:1], 1, v[92:93]
	v_lshl_add_u64 v[94:95], s[4:5], 0, v[0:1]
	v_cmp_lt_i32_e64 s[4:5], 0, v92
	v_add_u32_e32 v2, 64, v92
	v_ashrrev_i32_e32 v3, 31, v2
	v_writelane_b32 v253, s4, 13
	v_lshlrev_b64 v[6:7], 9, v[2:3]
	v_bfe_u32 v16, v92, 5, 1
	v_writelane_b32 v253, s5, 14
	v_cmp_lt_i32_e64 s[4:5], 1, v92
	v_and_b32_e32 v127, 31, v92
	v_lshlrev_b32_e32 v160, 3, v16
	v_writelane_b32 v253, s4, 15
	v_lshl_add_u64 v[106:107], s[2:3], 0, v[160:161]
	v_lshlrev_b64 v[4:5], 9, v[92:93]
	v_writelane_b32 v253, s5, 16
	v_cmp_lt_i32_e64 s[4:5], 2, v92
	v_cmp_gt_i32_e64 s[28:29], 4, v92
	v_ashrrev_i32_e32 v122, 3, v134
	v_writelane_b32 v253, s4, 19
	v_mul_lo_u32 v3, v122, s86
	v_lshl_add_u32 v8, v122, 1, 0
	v_writelane_b32 v253, s5, 20
	v_cmp_lt_i32_e64 s[4:5], 3, v92
	v_lshlrev_b32_e32 v129, 2, v16
	v_lshl_add_u32 v105, v92, 2, s21
	v_writelane_b32 v253, s4, 17
	v_bfe_u32 v126, v134, 6, 2
	v_or_b32_e32 v130, 2, v129
	v_writelane_b32 v253, s5, 18
	v_cmp_lt_i32_e64 s[4:5], 0, v2
	v_or_b32_e32 v131, 3, v129
	v_or_b32_e32 v132, 8, v129
	v_writelane_b32 v253, s4, 21
	v_or_b32_e32 v133, 9, v129
	v_or_b32_e32 v135, 10, v129
	v_writelane_b32 v253, s5, 22
	v_cmp_lt_i32_e64 s[4:5], 1, v2
	v_or_b32_e32 v136, 11, v129
	v_or_b32_e32 v137, 16, v129
	v_writelane_b32 v253, s4, 23
	v_or_b32_e32 v138, 17, v129
	v_or_b32_e32 v139, 18, v129
	v_writelane_b32 v253, s5, 24
	v_cmp_lt_i32_e64 s[4:5], 2, v2
	v_or_b32_e32 v140, 19, v129
	v_or_b32_e32 v141, 24, v129
	v_writelane_b32 v253, s4, 25
	v_or_b32_e32 v142, 25, v129
	v_or_b32_e32 v143, 26, v129
	v_writelane_b32 v253, s5, 26
	v_cmp_lt_i32_e64 s[4:5], 3, v2
	v_or_b32_e32 v144, 27, v129
	s_nop 0
	v_writelane_b32 v253, s4, 27
	s_nop 1
	v_writelane_b32 v253, s5, 28
	v_cmp_gt_i32_e64 s[4:5], 1, v92
	s_nop 1
	v_writelane_b32 v253, s4, 29
	s_nop 1
	v_writelane_b32 v253, s5, 30
	v_cmp_gt_i32_e64 s[4:5], 2, v92
	s_nop 1
	v_writelane_b32 v253, s4, 31
	s_nop 1
	v_writelane_b32 v253, s5, 32
	v_cmp_eq_u32_e64 s[4:5], 3, v92
	s_nop 1
	v_writelane_b32 v253, s4, 33
	s_nop 1
	v_writelane_b32 v253, s5, 34
	s_lshl_b32 s4, s6, 2
	s_add_u32 s4, s12, s4
	v_writelane_b32 v254, s12, 3
	s_addc_u32 s5, s13, 0
	v_writelane_b32 v253, s4, 35
	v_writelane_b32 v254, s13, 4
	s_nop 0
	v_writelane_b32 v253, s5, 36
	s_lshl_b32 s4, s10, 5
	s_and_b32 s6, s4, 0x80
	s_add_u32 s4, s26, s6
	s_addc_u32 s5, s27, 0
	v_lshl_add_u64 v[96:97], s[4:5], 0, v[0:1]
	s_add_u32 s4, s2, s7
	s_addc_u32 s5, s3, 0
	v_lshl_add_u64 v[98:99], s[4:5], 0, v[0:1]
	v_and_b32_e32 v0, 7, v92
	v_lshl_add_u32 v2, v0, 4, 0
	v_lshlrev_b32_e32 v100, 3, v0
	v_mul_u32_u24_e32 v9, 0x1080, v0
	v_add_u32_e32 v0, 0x200, v134
	v_ashrrev_i32_e32 v123, 3, v0
	v_add_u32_e32 v0, 0x400, v134
	v_ashrrev_i32_e32 v124, 3, v0
	v_add_u32_e32 v0, 0x600, v134
	v_ashrrev_i32_e32 v125, 3, v0
	v_ashrrev_i32_e32 v0, 2, v134
	v_and_b32_e32 v128, 0xffffffc0, v0
	v_lshlrev_b32_e32 v0, 4, v16
	v_mov_b32_e32 v1, v161
	v_lshl_add_u64 v[102:103], s[0:1], 0, v[0:1]
	s_movk_i32 s0, 0x210
	v_mad_u32_u24 v149, v127, s0, 0
	v_readlane_b32 s0, v254, 1
	s_sub_i32 s25, s0, 64
	s_lshl_b32 s0, s10, 6
	s_and_b32 s2, s0, 0x100
	v_readlane_b32 s0, v253, 3
	v_readlane_b32 s1, v253, 4
	s_add_u32 s0, s2, s0
	s_addc_u32 s1, 0, s1
	v_lshl_add_u64 v[108:109], s[0:1], 0, v[4:5]
	v_lshl_add_u64 v[110:111], s[0:1], 0, v[6:7]
	s_add_u32 s0, s8, s6
	v_writelane_b32 v254, s74, 14
	s_addc_u32 s1, s9, 0
	v_writelane_b32 v253, s0, 43
	v_writelane_b32 v254, s75, 15
	v_writelane_b32 v254, s21, 5
	v_writelane_b32 v253, s1, 44
	s_add_i32 s0, s21, 0x400
	v_writelane_b32 v254, s22, 7
	v_writelane_b32 v253, s0, 39
	v_mul_lo_u32 v10, v123, s86
	v_writelane_b32 v254, s23, 8
	v_readlane_b32 s0, v253, 5
	v_writelane_b32 v254, s26, 9
	v_readlane_b32 s1, v253, 6
	s_add_u32 s0, s0, s2
	v_writelane_b32 v253, s96, 60
	v_writelane_b32 v254, s27, 10
	v_lshl_add_u32 v11, v123, 1, 0
	v_mul_lo_u32 v12, v124, s86
	v_lshl_add_u32 v13, v124, 1, 0
	v_mul_lo_u32 v14, v125, s86
	v_lshl_add_u32 v15, v125, 1, 0
	s_addc_u32 s1, s1, 0
	v_writelane_b32 v253, s97, 61
	v_writelane_b32 v254, s28, 11
	v_add_u32_e32 v104, 0, v0
	v_add_u32_e32 v145, 64, v128
	v_add_u32_e32 v146, 0x60, v128
	v_add_u32_e32 v147, 0x80, v128
	v_or_b32_e32 v148, 32, v128
	v_lshl_add_u64 v[112:113], v[92:93], 2, s[0:1]
	v_add_u32_e32 v93, v2, v3
	v_add_u32_e32 v150, v8, v9
	v_add_u32_e32 v151, v2, v10
	v_add_u32_e32 v152, v11, v9
	v_add_u32_e32 v153, v2, v12
	v_add_u32_e32 v154, v13, v9
	v_add_u32_e32 v155, v2, v14
	v_add_u32_e32 v156, v15, v9
	v_writelane_b32 v254, s29, 12
	v_writelane_b32 v253, s25, 37
	s_branch .LBB0_1038

;     __device__ __forceinline__ void operator()(const Acc& acc, const Unit& u, int wr, int wc, int fr, int fq) const {
;     ...
;                         } else *(f32x4*)(X + (size_t)row * D + col) = *(const f32x4*)(base + col) + ga; } }
; template <bool FINAL>
; __device__ __forceinline__ void norm_rows(const float* xp, const float* xs, const float* X, const float* g, const float* sh, const float* sc, bf16_t* XN, float* out, int gw, int NGW, int lane, const float* part, int nsplit) {
;     ...
;         const float rstd = 1.0f / sqrtf(wave_sum(s) * (1.0f / D) + EPS);
.Lfz_out_nopub:
	s_waitcnt vmcnt(0)
	s_barrier
	v_mov_b32_e32 v140, 0x20450
	ds_read_b64 v[140:141], v140
	s_waitcnt lgkmcnt(0)
	v_readfirstlane_b32 s2, v140
	v_readfirstlane_b32 s3, v141
	s_add_i32 s74, s96, 0
	s_lshl_b32 s74, s74, 12
	s_add_u32 s2, s2, s74
	s_addc_u32 s3, s3, 0
	s_nop 4
	global_load_dwordx4 v[208:211], v159, s[2:3]
	global_load_dwordx4 v[212:215], v159, s[2:3] offset:64
	global_load_dwordx4 v[216:219], v159, s[2:3] offset:512
	global_load_dwordx4 v[220:223], v159, s[2:3] offset:576
	s_mov_b32 s74, 0x1000
	v_add_co_u32_e32 v130, vcc, s74, v130
	s_nop 1
	v_addc_co_u32_e32 v131, vcc, 0, v131, vcc
	global_load_dwordx4 v[240:243], v[130:131], off
	global_load_dwordx4 v[244:247], v[130:131], off offset:64
	global_load_dwordx4 v[248:251], v[130:131], off offset:512
	global_load_dwordx4 v[184:187], v[130:131], off offset:576
	v_add_co_u32_e32 v130, vcc, 0x1000, v130
	s_nop 1
	v_addc_co_u32_e32 v131, vcc, 0, v131, vcc
	global_load_dwordx4 v[224:227], v[130:131], off
	global_load_dwordx4 v[228:231], v[130:131], off offset:64
	global_load_dwordx4 v[232:235], v[130:131], off offset:512
	global_load_dwordx4 v[236:239], v[130:131], off offset:576
	global_store_dwordx4 v[146:147], v[124:127], off
	global_store_dwordx4 v[146:147], v[120:123], off offset:64
	global_store_dwordx4 v[146:147], v[116:119], off offset:512
	global_store_dwordx4 v[146:147], v[112:115], off offset:576
	v_lshl_add_u64 v[146:147], v[146:147], 0, s[66:67]
	global_store_dwordx4 v[146:147], v[108:111], off
	global_store_dwordx4 v[146:147], v[104:107], off offset:64
	global_store_dwordx4 v[146:147], v[100:103], off offset:512
	global_store_dwordx4 v[146:147], v[96:99], off offset:576
	v_lshl_add_u64 v[146:147], v[146:147], 0, s[66:67]
	global_store_dwordx4 v[146:147], v[92:95], off
	global_store_dwordx4 v[146:147], v[88:91], off offset:64
	global_store_dwordx4 v[146:147], v[84:87], off offset:512
	global_store_dwordx4 v[146:147], v[80:83], off offset:576
	v_lshl_add_u64 v[146:147], v[146:147], 0, s[66:67]
	global_store_dwordx4 v[146:147], v[76:79], off
	global_store_dwordx4 v[146:147], v[72:75], off offset:64
	global_store_dwordx4 v[146:147], v[68:71], off offset:512
	global_store_dwordx4 v[146:147], v[64:67], off offset:576
	v_lshl_add_u64 v[146:147], v[146:147], 0, s[68:69]
	global_store_dwordx4 v[146:147], v[60:63], off
	global_store_dwordx4 v[146:147], v[56:59], off offset:64
	global_store_dwordx4 v[146:147], v[52:55], off offset:512
	global_store_dwordx4 v[146:147], v[48:51], off offset:576
	v_lshl_add_u64 v[146:147], v[146:147], 0, s[66:67]
	global_store_dwordx4 v[146:147], v[44:47], off
	global_store_dwordx4 v[146:147], v[40:43], off offset:64
	global_store_dwordx4 v[146:147], v[36:39], off offset:512
	global_store_dwordx4 v[146:147], v[32:35], off offset:576
	v_lshl_add_u64 v[146:147], v[146:147], 0, s[66:67]
	global_store_dwordx4 v[146:147], v[28:31], off
	global_store_dwordx4 v[146:147], v[24:27], off offset:64
	global_store_dwordx4 v[146:147], v[20:23], off offset:512
	global_store_dwordx4 v[146:147], v[16:19], off offset:576
	v_lshl_add_u64 v[146:147], v[146:147], 0, s[66:67]
	global_store_dwordx4 v[146:147], v[12:15], off
	global_store_dwordx4 v[146:147], v[8:11], off offset:64
	global_store_dwordx4 v[146:147], v[4:7], off offset:512
	global_store_dwordx4 v[146:147], v[0:3], off offset:576
	s_cmp_eq_u32 s25, 0
	s_cbranch_scc0 .Lfz_out_nopoll
	s_mov_b64 exec, 1
	v_mov_b32_e32 v140, 0
	v_mov_b32_e32 v141, 1
	global_atomic_add v140, v141, s[98:99]
	s_mov_b32 s65, 0

; template <bool FINAL>
; __device__ __forceinline__ void norm_rows(const float* xp, const float* xs, const float* X, const float* g, const float* sh, const float* sc, bf16_t* XN, float* out, int gw, int NGW, int lane, const float* part, int nsplit) {
;     ...
;         const float rstd = 1.0f / sqrtf(wave_sum(s) * (1.0f / D) + EPS);
.Lfz_out_polled:
	s_mov_b64 exec, -1

; __device__ __forceinline__ unsigned cvt_pk_bf16(float lo, float hi) { const f32x2_t v = {lo, hi}; const bf16x2_t b = __builtin_convertvector(v, bf16x2_t); return __builtin_bit_cast(unsigned, b); }
; template <bool FINAL>
; __device__ __forceinline__ void norm_rows(const float* xp, const float* xs, const float* X, const float* g, const float* sh, const float* sc, bf16_t* XN, float* out, int gw, int NGW, int lane, const float* part, int nsplit) {
;     ...
;         for (int j = 0; j < 4; ++j) { const int col = 4 * lane + 256 * j; const f32x4 gg = *(const f32x4*)(g + col);
;             if (FINAL) { *(f32x4*)(out + (size_t)row * D + col) = v[j] * rstd * gg; }
;             else { const f32x4 s1 = *(const f32x4*)(sc + (size_t)mr * 6144 + col), s0 = *(const f32x4*)(sh + (size_t)mr * 6144 + col);
;                 const f32x4 h = v[j] * rstd * gg * (s1 + 1.0f) + s0;
;                 *(u32x2*)(XN + (size_t)row * D + col) = (u32x2){cvt_pk_bf16(h[0], h[1]), cvt_pk_bf16(h[2], h[3])}; } }
.Lfz_out_norstd:
	s_waitcnt lgkmcnt(0)
	s_barrier
	v_lshlrev_b32_e32 v130, 2, v142
	v_add_u32_e32 v130, 0x21800, v130
	ds_read_b32 v188, v130
	ds_read_b32 v189, v130 offset:64
	ds_read_b32 v190, v130 offset:128
	ds_read_b32 v191, v130 offset:192
	ds_read_b32 v192, v130 offset:512
	ds_read_b32 v193, v130 offset:576
	ds_read_b32 v194, v130 offset:640
	ds_read_b32 v195, v130 offset:704
	s_waitcnt vmcnt(0) lgkmcnt(0)
	v_pk_add_f32 v[226:227], v[226:227], 1.0 op_sel_hi:[1,0]
	v_pk_add_f32 v[224:225], v[224:225], 1.0 op_sel_hi:[1,0]
	v_pk_add_f32 v[230:231], v[230:231], 1.0 op_sel_hi:[1,0]
	v_pk_add_f32 v[228:229], v[228:229], 1.0 op_sel_hi:[1,0]
	v_pk_add_f32 v[234:235], v[234:235], 1.0 op_sel_hi:[1,0]
	v_pk_add_f32 v[232:233], v[232:233], 1.0 op_sel_hi:[1,0]
	v_pk_add_f32 v[238:239], v[238:239], 1.0 op_sel_hi:[1,0]
	v_pk_add_f32 v[236:237], v[236:237], 1.0 op_sel_hi:[1,0]
	v_mul_f32_e32 v124, v124, v188
	v_mul_f32_e32 v125, v125, v188
	v_mul_f32_e32 v126, v126, v188
	v_mul_f32_e32 v127, v127, v188
	v_pk_mul_f32 v[124:125], v[208:209], v[124:125]
	v_pk_mul_f32 v[126:127], v[210:211], v[126:127]
	v_pk_fma_f32 v[126:127], v[226:227], v[126:127], v[242:243]
	v_pk_fma_f32 v[124:125], v[224:225], v[124:125], v[240:241]
	s_nop 0
	v_cvt_pk_bf16_f32 v124, v124, v125
	v_cvt_pk_bf16_f32 v125, v126, v127
	global_store_dwordx2 v[128:129], v[124:125], off
	v_mul_f32_e32 v120, v120, v188
	v_mul_f32_e32 v121, v121, v188
	v_mul_f32_e32 v122, v122, v188
	v_mul_f32_e32 v123, v123, v188
	v_pk_mul_f32 v[120:121], v[212:213], v[120:121]
	v_pk_mul_f32 v[122:123], v[214:215], v[122:123]
	v_pk_fma_f32 v[122:123], v[230:231], v[122:123], v[246:247]
	v_pk_fma_f32 v[120:121], v[228:229], v[120:121], v[244:245]
	s_nop 0
	v_cvt_pk_bf16_f32 v120, v120, v121
	v_cvt_pk_bf16_f32 v121, v122, v123
	global_store_dwordx2 v[128:129], v[120:121], off offset:32
	v_mul_f32_e32 v116, v116, v188
	v_mul_f32_e32 v117, v117, v188
	v_mul_f32_e32 v118, v118, v188
	v_mul_f32_e32 v119, v119, v188
	v_pk_mul_f32 v[116:117], v[216:217], v[116:117]
	v_pk_mul_f32 v[118:119], v[218:219], v[118:119]
	v_pk_fma_f32 v[118:119], v[234:235], v[118:119], v[250:251]
	v_pk_fma_f32 v[116:117], v[232:233], v[116:117], v[248:249]
	s_nop 0
	v_cvt_pk_bf16_f32 v116, v116, v117
	v_cvt_pk_bf16_f32 v117, v118, v119
	global_store_dwordx2 v[128:129], v[116:117], off offset:256
	v_mul_f32_e32 v112, v112, v188
	v_mul_f32_e32 v113, v113, v188
	v_mul_f32_e32 v114, v114, v188
	v_mul_f32_e32 v115, v115, v188
	v_pk_mul_f32 v[112:113], v[220:221], v[112:113]
	v_pk_mul_f32 v[114:115], v[222:223], v[114:115]
	v_pk_fma_f32 v[114:115], v[238:239], v[114:115], v[186:187]
	v_pk_fma_f32 v[112:113], v[236:237], v[112:113], v[184:185]
	s_nop 0
	v_cvt_pk_bf16_f32 v112, v112, v113
	v_cvt_pk_bf16_f32 v113, v114, v115
	global_store_dwordx2 v[128:129], v[112:113], off offset:288
	v_add_co_u32_e32 v128, vcc, 0x8000, v128
	s_nop 1
	v_addc_co_u32_e32 v129, vcc, 0, v129, vcc
	v_mul_f32_e32 v108, v108, v189
	v_mul_f32_e32 v109, v109, v189
	v_mul_f32_e32 v110, v110, v189
	v_mul_f32_e32 v111, v111, v189
	v_pk_mul_f32 v[108:109], v[208:209], v[108:109]
	v_pk_mul_f32 v[110:111], v[210:211], v[110:111]
	v_pk_fma_f32 v[110:111], v[226:227], v[110:111], v[242:243]
	v_pk_fma_f32 v[108:109], v[224:225], v[108:109], v[240:241]
	s_nop 0
	v_cvt_pk_bf16_f32 v108, v108, v109
	v_cvt_pk_bf16_f32 v109, v110, v111
	global_store_dwordx2 v[128:129], v[108:109], off
	v_mul_f32_e32 v104, v104, v189
	v_mul_f32_e32 v105, v105, v189
	v_mul_f32_e32 v106, v106, v189
	v_mul_f32_e32 v107, v107, v189
	v_pk_mul_f32 v[104:105], v[212:213], v[104:105]
	v_pk_mul_f32 v[106:107], v[214:215], v[106:107]
	v_pk_fma_f32 v[106:107], v[230:231], v[106:107], v[246:247]
	v_pk_fma_f32 v[104:105], v[228:229], v[104:105], v[244:245]
	s_nop 0
	v_cvt_pk_bf16_f32 v104, v104, v105
	v_cvt_pk_bf16_f32 v105, v106, v107
	global_store_dwordx2 v[128:129], v[104:105], off offset:32
	v_mul_f32_e32 v100, v100, v189
	v_mul_f32_e32 v101, v101, v189
	v_mul_f32_e32 v102, v102, v189
	v_mul_f32_e32 v103, v103, v189
	v_pk_mul_f32 v[100:101], v[216:217], v[100:101]
	v_pk_mul_f32 v[102:103], v[218:219], v[102:103]
	v_pk_fma_f32 v[102:103], v[234:235], v[102:103], v[250:251]
	v_pk_fma_f32 v[100:101], v[232:233], v[100:101], v[248:249]
	s_nop 0
	v_cvt_pk_bf16_f32 v100, v100, v101
	v_cvt_pk_bf16_f32 v101, v102, v103
	global_store_dwordx2 v[128:129], v[100:101], off offset:256
	v_mul_f32_e32 v96, v96, v189
	v_mul_f32_e32 v97, v97, v189
	v_mul_f32_e32 v98, v98, v189
	v_mul_f32_e32 v99, v99, v189
	v_pk_mul_f32 v[96:97], v[220:221], v[96:97]
	v_pk_mul_f32 v[98:99], v[222:223], v[98:99]
	v_pk_fma_f32 v[98:99], v[238:239], v[98:99], v[186:187]
	v_pk_fma_f32 v[96:97], v[236:237], v[96:97], v[184:185]
	s_nop 0
	v_cvt_pk_bf16_f32 v96, v96, v97
	v_cvt_pk_bf16_f32 v97, v98, v99
	global_store_dwordx2 v[128:129], v[96:97], off offset:288
	v_add_co_u32_e32 v128, vcc, 0x8000, v128
	s_nop 1
	v_addc_co_u32_e32 v129, vcc, 0, v129, vcc
	v_mul_f32_e32 v92, v92, v190
	v_mul_f32_e32 v93, v93, v190
	v_mul_f32_e32 v94, v94, v190
	v_mul_f32_e32 v95, v95, v190
	v_pk_mul_f32 v[92:93], v[208:209], v[92:93]
	v_pk_mul_f32 v[94:95], v[210:211], v[94:95]
	v_pk_fma_f32 v[94:95], v[226:227], v[94:95], v[242:243]
	v_pk_fma_f32 v[92:93], v[224:225], v[92:93], v[240:241]
	s_nop 0
	v_cvt_pk_bf16_f32 v92, v92, v93
	v_cvt_pk_bf16_f32 v93, v94, v95
	global_store_dwordx2 v[128:129], v[92:93], off
	v_mul_f32_e32 v88, v88, v190
	v_mul_f32_e32 v89, v89, v190
	v_mul_f32_e32 v90, v90, v190
	v_mul_f32_e32 v91, v91, v190
	v_pk_mul_f32 v[88:89], v[212:213], v[88:89]
	v_pk_mul_f32 v[90:91], v[214:215], v[90:91]
	v_pk_fma_f32 v[90:91], v[230:231], v[90:91], v[246:247]
; __device__ __forceinline__ unsigned cvt_pk_bf16(float lo, float hi) { const f32x2_t v = {lo, hi}; const bf16x2_t b = __builtin_convertvector(v, bf16x2_t); return __builtin_bit_cast(unsigned, b); }
; template <bool FINAL>
; __device__ __forceinline__ void norm_rows(const float* xp, const float* xs, const float* X, const float* g, const float* sh, const float* sc, bf16_t* XN, float* out, int gw, int NGW, int lane, const float* part, int nsplit) {
;     ...
;         for (int j = 0; j < 4; ++j) { const int col = 4 * lane + 256 * j; const f32x4 gg = *(const f32x4*)(g + col);
;             if (FINAL) { *(f32x4*)(out + (size_t)row * D + col) = v[j] * rstd * gg; }
;             else { const f32x4 s1 = *(const f32x4*)(sc + (size_t)mr * 6144 + col), s0 = *(const f32x4*)(sh + (size_t)mr * 6144 + col);
;                 const f32x4 h = v[j] * rstd * gg * (s1 + 1.0f) + s0;
;                 *(u32x2*)(XN + (size_t)row * D + col) = (u32x2){cvt_pk_bf16(h[0], h[1]), cvt_pk_bf16(h[2], h[3])}; } }
	v_pk_fma_f32 v[88:89], v[228:229], v[88:89], v[244:245]
	s_nop 0
	v_cvt_pk_bf16_f32 v88, v88, v89
	v_cvt_pk_bf16_f32 v89, v90, v91
	global_store_dwordx2 v[128:129], v[88:89], off offset:32
	v_mul_f32_e32 v84, v84, v190
	v_mul_f32_e32 v85, v85, v190
	v_mul_f32_e32 v86, v86, v190
	v_mul_f32_e32 v87, v87, v190
	v_pk_mul_f32 v[84:85], v[216:217], v[84:85]
	v_pk_mul_f32 v[86:87], v[218:219], v[86:87]
	v_pk_fma_f32 v[86:87], v[234:235], v[86:87], v[250:251]
	v_pk_fma_f32 v[84:85], v[232:233], v[84:85], v[248:249]
	s_nop 0
	v_cvt_pk_bf16_f32 v84, v84, v85
	v_cvt_pk_bf16_f32 v85, v86, v87
	global_store_dwordx2 v[128:129], v[84:85], off offset:256
	v_mul_f32_e32 v80, v80, v190
	v_mul_f32_e32 v81, v81, v190
	v_mul_f32_e32 v82, v82, v190
	v_mul_f32_e32 v83, v83, v190
	v_pk_mul_f32 v[80:81], v[220:221], v[80:81]
	v_pk_mul_f32 v[82:83], v[222:223], v[82:83]
	v_pk_fma_f32 v[82:83], v[238:239], v[82:83], v[186:187]
	v_pk_fma_f32 v[80:81], v[236:237], v[80:81], v[184:185]
	s_nop 0
	v_cvt_pk_bf16_f32 v80, v80, v81
	v_cvt_pk_bf16_f32 v81, v82, v83
	global_store_dwordx2 v[128:129], v[80:81], off offset:288
	v_add_co_u32_e32 v128, vcc, 0x8000, v128
	s_nop 1
	v_addc_co_u32_e32 v129, vcc, 0, v129, vcc
	v_mul_f32_e32 v76, v76, v191
	v_mul_f32_e32 v77, v77, v191
	v_mul_f32_e32 v78, v78, v191
	v_mul_f32_e32 v79, v79, v191
	v_pk_mul_f32 v[76:77], v[208:209], v[76:77]
	v_pk_mul_f32 v[78:79], v[210:211], v[78:79]
	v_pk_fma_f32 v[78:79], v[226:227], v[78:79], v[242:243]
	v_pk_fma_f32 v[76:77], v[224:225], v[76:77], v[240:241]
	s_nop 0
	v_cvt_pk_bf16_f32 v76, v76, v77
	v_cvt_pk_bf16_f32 v77, v78, v79
	global_store_dwordx2 v[128:129], v[76:77], off
	v_mul_f32_e32 v72, v72, v191
	v_mul_f32_e32 v73, v73, v191
	v_mul_f32_e32 v74, v74, v191
	v_mul_f32_e32 v75, v75, v191
	v_pk_mul_f32 v[72:73], v[212:213], v[72:73]
	v_pk_mul_f32 v[74:75], v[214:215], v[74:75]
	v_pk_fma_f32 v[74:75], v[230:231], v[74:75], v[246:247]
	v_pk_fma_f32 v[72:73], v[228:229], v[72:73], v[244:245]
	s_nop 0
	v_cvt_pk_bf16_f32 v72, v72, v73
	v_cvt_pk_bf16_f32 v73, v74, v75
	global_store_dwordx2 v[128:129], v[72:73], off offset:32
	v_mul_f32_e32 v68, v68, v191
	v_mul_f32_e32 v69, v69, v191
	v_mul_f32_e32 v70, v70, v191
	v_mul_f32_e32 v71, v71, v191
	v_pk_mul_f32 v[68:69], v[216:217], v[68:69]
	v_pk_mul_f32 v[70:71], v[218:219], v[70:71]
	v_pk_fma_f32 v[70:71], v[234:235], v[70:71], v[250:251]
	v_pk_fma_f32 v[68:69], v[232:233], v[68:69], v[248:249]
	s_nop 0
	v_cvt_pk_bf16_f32 v68, v68, v69
	v_cvt_pk_bf16_f32 v69, v70, v71
	global_store_dwordx2 v[128:129], v[68:69], off offset:256
	v_mul_f32_e32 v64, v64, v191
	v_mul_f32_e32 v65, v65, v191
	v_mul_f32_e32 v66, v66, v191
	v_mul_f32_e32 v67, v67, v191
	v_pk_mul_f32 v[64:65], v[220:221], v[64:65]
	v_pk_mul_f32 v[66:67], v[222:223], v[66:67]
	v_pk_fma_f32 v[66:67], v[238:239], v[66:67], v[186:187]
	v_pk_fma_f32 v[64:65], v[236:237], v[64:65], v[184:185]
	s_nop 0
	v_cvt_pk_bf16_f32 v64, v64, v65
	v_cvt_pk_bf16_f32 v65, v66, v67
	global_store_dwordx2 v[128:129], v[64:65], off offset:288
	v_add_co_u32_e32 v128, vcc, 0x28000, v128
	s_nop 1
	v_addc_co_u32_e32 v129, vcc, 0, v129, vcc
	v_mul_f32_e32 v60, v60, v192
	v_mul_f32_e32 v61, v61, v192
	v_mul_f32_e32 v62, v62, v192
	v_mul_f32_e32 v63, v63, v192
	v_pk_mul_f32 v[60:61], v[208:209], v[60:61]
	v_pk_mul_f32 v[62:63], v[210:211], v[62:63]
	v_pk_fma_f32 v[62:63], v[226:227], v[62:63], v[242:243]
	v_pk_fma_f32 v[60:61], v[224:225], v[60:61], v[240:241]
	s_nop 0
	v_cvt_pk_bf16_f32 v60, v60, v61
	v_cvt_pk_bf16_f32 v61, v62, v63
	global_store_dwordx2 v[128:129], v[60:61], off
	v_mul_f32_e32 v56, v56, v192
	v_mul_f32_e32 v57, v57, v192
	v_mul_f32_e32 v58, v58, v192
	v_mul_f32_e32 v59, v59, v192
	v_pk_mul_f32 v[56:57], v[212:213], v[56:57]
	v_pk_mul_f32 v[58:59], v[214:215], v[58:59]
	v_pk_fma_f32 v[58:59], v[230:231], v[58:59], v[246:247]
	v_pk_fma_f32 v[56:57], v[228:229], v[56:57], v[244:245]
	s_nop 0
	v_cvt_pk_bf16_f32 v56, v56, v57
	v_cvt_pk_bf16_f32 v57, v58, v59
	global_store_dwordx2 v[128:129], v[56:57], off offset:32
	v_mul_f32_e32 v52, v52, v192
	v_mul_f32_e32 v53, v53, v192
	v_mul_f32_e32 v54, v54, v192
	v_mul_f32_e32 v55, v55, v192
	v_pk_mul_f32 v[52:53], v[216:217], v[52:53]
	v_pk_mul_f32 v[54:55], v[218:219], v[54:55]
	v_pk_fma_f32 v[54:55], v[234:235], v[54:55], v[250:251]
	v_pk_fma_f32 v[52:53], v[232:233], v[52:53], v[248:249]
	s_nop 0
	v_cvt_pk_bf16_f32 v52, v52, v53
	v_cvt_pk_bf16_f32 v53, v54, v55
	global_store_dwordx2 v[128:129], v[52:53], off offset:256
	v_mul_f32_e32 v48, v48, v192
	v_mul_f32_e32 v49, v49, v192
	v_mul_f32_e32 v50, v50, v192
	v_mul_f32_e32 v51, v51, v192
	v_pk_mul_f32 v[48:49], v[220:221], v[48:49]
	v_pk_mul_f32 v[50:51], v[222:223], v[50:51]
	v_pk_fma_f32 v[50:51], v[238:239], v[50:51], v[186:187]
	v_pk_fma_f32 v[48:49], v[236:237], v[48:49], v[184:185]
	s_nop 0
	v_cvt_pk_bf16_f32 v48, v48, v49
	v_cvt_pk_bf16_f32 v49, v50, v51
	global_store_dwordx2 v[128:129], v[48:49], off offset:288
	v_add_co_u32_e32 v128, vcc, 0x8000, v128
	s_nop 1
	v_addc_co_u32_e32 v129, vcc, 0, v129, vcc
	v_mul_f32_e32 v44, v44, v193
	v_mul_f32_e32 v45, v45, v193
	v_mul_f32_e32 v46, v46, v193
	v_mul_f32_e32 v47, v47, v193
	v_pk_mul_f32 v[44:45], v[208:209], v[44:45]
	v_pk_mul_f32 v[46:47], v[210:211], v[46:47]
	v_pk_fma_f32 v[46:47], v[226:227], v[46:47], v[242:243]
; __device__ __forceinline__ unsigned cvt_pk_bf16(float lo, float hi) { const f32x2_t v = {lo, hi}; const bf16x2_t b = __builtin_convertvector(v, bf16x2_t); return __builtin_bit_cast(unsigned, b); }
; template <bool FINAL>
; __device__ __forceinline__ void norm_rows(const float* xp, const float* xs, const float* X, const float* g, const float* sh, const float* sc, bf16_t* XN, float* out, int gw, int NGW, int lane, const float* part, int nsplit) {
;     ...
;         for (int j = 0; j < 4; ++j) { const int col = 4 * lane + 256 * j; const f32x4 gg = *(const f32x4*)(g + col);
;             if (FINAL) { *(f32x4*)(out + (size_t)row * D + col) = v[j] * rstd * gg; }
;             else { const f32x4 s1 = *(const f32x4*)(sc + (size_t)mr * 6144 + col), s0 = *(const f32x4*)(sh + (size_t)mr * 6144 + col);
;                 const f32x4 h = v[j] * rstd * gg * (s1 + 1.0f) + s0;
;                 *(u32x2*)(XN + (size_t)row * D + col) = (u32x2){cvt_pk_bf16(h[0], h[1]), cvt_pk_bf16(h[2], h[3])}; } }
	v_pk_fma_f32 v[44:45], v[224:225], v[44:45], v[240:241]
	s_nop 0
	v_cvt_pk_bf16_f32 v44, v44, v45
	v_cvt_pk_bf16_f32 v45, v46, v47
	global_store_dwordx2 v[128:129], v[44:45], off
	v_mul_f32_e32 v40, v40, v193
	v_mul_f32_e32 v41, v41, v193
	v_mul_f32_e32 v42, v42, v193
	v_mul_f32_e32 v43, v43, v193
	v_pk_mul_f32 v[40:41], v[212:213], v[40:41]
	v_pk_mul_f32 v[42:43], v[214:215], v[42:43]
	v_pk_fma_f32 v[42:43], v[230:231], v[42:43], v[246:247]
	v_pk_fma_f32 v[40:41], v[228:229], v[40:41], v[244:245]
	s_nop 0
	v_cvt_pk_bf16_f32 v40, v40, v41
	v_cvt_pk_bf16_f32 v41, v42, v43
	global_store_dwordx2 v[128:129], v[40:41], off offset:32
	v_mul_f32_e32 v36, v36, v193
	v_mul_f32_e32 v37, v37, v193
	v_mul_f32_e32 v38, v38, v193
	v_mul_f32_e32 v39, v39, v193
	v_pk_mul_f32 v[36:37], v[216:217], v[36:37]
	v_pk_mul_f32 v[38:39], v[218:219], v[38:39]
	v_pk_fma_f32 v[38:39], v[234:235], v[38:39], v[250:251]
	v_pk_fma_f32 v[36:37], v[232:233], v[36:37], v[248:249]
	s_nop 0
	v_cvt_pk_bf16_f32 v36, v36, v37
	v_cvt_pk_bf16_f32 v37, v38, v39
	global_store_dwordx2 v[128:129], v[36:37], off offset:256
	v_mul_f32_e32 v32, v32, v193
	v_mul_f32_e32 v33, v33, v193
	v_mul_f32_e32 v34, v34, v193
	v_mul_f32_e32 v35, v35, v193
	v_pk_mul_f32 v[32:33], v[220:221], v[32:33]
	v_pk_mul_f32 v[34:35], v[222:223], v[34:35]
	v_pk_fma_f32 v[34:35], v[238:239], v[34:35], v[186:187]
	v_pk_fma_f32 v[32:33], v[236:237], v[32:33], v[184:185]
	s_nop 0
	v_cvt_pk_bf16_f32 v32, v32, v33
	v_cvt_pk_bf16_f32 v33, v34, v35
	global_store_dwordx2 v[128:129], v[32:33], off offset:288
	v_add_co_u32_e32 v128, vcc, 0x8000, v128
	s_nop 1
	v_addc_co_u32_e32 v129, vcc, 0, v129, vcc
	v_mul_f32_e32 v28, v28, v194
	v_mul_f32_e32 v29, v29, v194
	v_mul_f32_e32 v30, v30, v194
	v_mul_f32_e32 v31, v31, v194
	v_pk_mul_f32 v[28:29], v[208:209], v[28:29]
	v_pk_mul_f32 v[30:31], v[210:211], v[30:31]
	v_pk_fma_f32 v[30:31], v[226:227], v[30:31], v[242:243]
	v_pk_fma_f32 v[28:29], v[224:225], v[28:29], v[240:241]
	s_nop 0
	v_cvt_pk_bf16_f32 v28, v28, v29
	v_cvt_pk_bf16_f32 v29, v30, v31
	global_store_dwordx2 v[128:129], v[28:29], off
	v_mul_f32_e32 v24, v24, v194
	v_mul_f32_e32 v25, v25, v194
	v_mul_f32_e32 v26, v26, v194
	v_mul_f32_e32 v27, v27, v194
	v_pk_mul_f32 v[24:25], v[212:213], v[24:25]
	v_pk_mul_f32 v[26:27], v[214:215], v[26:27]
	v_pk_fma_f32 v[26:27], v[230:231], v[26:27], v[246:247]
	v_pk_fma_f32 v[24:25], v[228:229], v[24:25], v[244:245]
	s_nop 0
	v_cvt_pk_bf16_f32 v24, v24, v25
	v_cvt_pk_bf16_f32 v25, v26, v27
	global_store_dwordx2 v[128:129], v[24:25], off offset:32
	v_mul_f32_e32 v20, v20, v194
	v_mul_f32_e32 v21, v21, v194
	v_mul_f32_e32 v22, v22, v194
	v_mul_f32_e32 v23, v23, v194
	v_pk_mul_f32 v[20:21], v[216:217], v[20:21]
	v_pk_mul_f32 v[22:23], v[218:219], v[22:23]
	v_pk_fma_f32 v[22:23], v[234:235], v[22:23], v[250:251]
	v_pk_fma_f32 v[20:21], v[232:233], v[20:21], v[248:249]
	s_nop 0
	v_cvt_pk_bf16_f32 v20, v20, v21
	v_cvt_pk_bf16_f32 v21, v22, v23
	global_store_dwordx2 v[128:129], v[20:21], off offset:256
	v_mul_f32_e32 v16, v16, v194
	v_mul_f32_e32 v17, v17, v194
	v_mul_f32_e32 v18, v18, v194
	v_mul_f32_e32 v19, v19, v194
	v_pk_mul_f32 v[16:17], v[220:221], v[16:17]
	v_pk_mul_f32 v[18:19], v[222:223], v[18:19]
	v_pk_fma_f32 v[18:19], v[238:239], v[18:19], v[186:187]
	v_pk_fma_f32 v[16:17], v[236:237], v[16:17], v[184:185]
	s_nop 0
	v_cvt_pk_bf16_f32 v16, v16, v17
	v_cvt_pk_bf16_f32 v17, v18, v19
	global_store_dwordx2 v[128:129], v[16:17], off offset:288
	v_add_co_u32_e32 v128, vcc, 0x8000, v128
	s_nop 1
	v_addc_co_u32_e32 v129, vcc, 0, v129, vcc
	v_mul_f32_e32 v12, v12, v195
	v_mul_f32_e32 v13, v13, v195
	v_mul_f32_e32 v14, v14, v195
	v_mul_f32_e32 v15, v15, v195
	v_pk_mul_f32 v[12:13], v[208:209], v[12:13]
	v_pk_mul_f32 v[14:15], v[210:211], v[14:15]
	v_pk_fma_f32 v[14:15], v[226:227], v[14:15], v[242:243]
	v_pk_fma_f32 v[12:13], v[224:225], v[12:13], v[240:241]
	s_nop 0
	v_cvt_pk_bf16_f32 v12, v12, v13
	v_cvt_pk_bf16_f32 v13, v14, v15
	global_store_dwordx2 v[128:129], v[12:13], off
	v_mul_f32_e32 v8, v8, v195
	v_mul_f32_e32 v9, v9, v195
	v_mul_f32_e32 v10, v10, v195
	v_mul_f32_e32 v11, v11, v195
	v_pk_mul_f32 v[8:9], v[212:213], v[8:9]
	v_pk_mul_f32 v[10:11], v[214:215], v[10:11]
	v_pk_fma_f32 v[10:11], v[230:231], v[10:11], v[246:247]
	v_pk_fma_f32 v[8:9], v[228:229], v[8:9], v[244:245]
	s_nop 0
	v_cvt_pk_bf16_f32 v8, v8, v9
	v_cvt_pk_bf16_f32 v9, v10, v11
	global_store_dwordx2 v[128:129], v[8:9], off offset:32
	v_mul_f32_e32 v4, v4, v195
	v_mul_f32_e32 v5, v5, v195
	v_mul_f32_e32 v6, v6, v195
	v_mul_f32_e32 v7, v7, v195
	v_pk_mul_f32 v[4:5], v[216:217], v[4:5]
	v_pk_mul_f32 v[6:7], v[218:219], v[6:7]
	v_pk_fma_f32 v[6:7], v[234:235], v[6:7], v[250:251]
	v_pk_fma_f32 v[4:5], v[232:233], v[4:5], v[248:249]
	s_nop 0
	v_cvt_pk_bf16_f32 v4, v4, v5
	v_cvt_pk_bf16_f32 v5, v6, v7
	global_store_dwordx2 v[128:129], v[4:5], off offset:256
	v_mul_f32_e32 v0, v0, v195
	v_mul_f32_e32 v1, v1, v195
	v_mul_f32_e32 v2, v2, v195
	v_mul_f32_e32 v3, v3, v195
	v_pk_mul_f32 v[0:1], v[220:221], v[0:1]
	v_pk_mul_f32 v[2:3], v[222:223], v[2:3]
	v_pk_fma_f32 v[2:3], v[238:239], v[2:3], v[186:187]
	v_pk_fma_f32 v[0:1], v[236:237], v[0:1], v[184:185]
	s_nop 0
	v_cvt_pk_bf16_f32 v0, v0, v1
	v_cvt_pk_bf16_f32 v1, v2, v3
	global_store_dwordx2 v[128:129], v[0:1], off offset:288
	s_branch .Lepi_out_done

;     __device__ __forceinline__ void operator()(const Acc& acc, const Unit& u, int wr, int wc, int fr, int fq) const {
;     ...
;                         } else *(f32x4*)(X + (size_t)row * D + col) = *(const f32x4*)(base + col) + ga; } }
; template <bool FINAL>
; __device__ __forceinline__ void norm_rows(const float* xp, const float* xs, const float* X, const float* g, const float* sh, const float* sc, bf16_t* XN, float* out, int gw, int NGW, int lane, const float* part, int nsplit) {
;     ...
;         for (int j = 0; j < 4; ++j) { const int col = 4 * lane + 256 * j; const f32x4 gg = *(const f32x4*)(g + col);
;             if (FINAL) { *(f32x4*)(out + (size_t)row * D + col) = v[j] * rstd * gg; }
;             else { const f32x4 s1 = *(const f32x4*)(sc + (size_t)mr * 6144 + col), s0 = *(const f32x4*)(sh + (size_t)mr * 6144 + col);
.Lfz_dn_nopub:
	s_waitcnt vmcnt(0)
	s_barrier
	v_mov_b32_e32 v140, 0x20448
	ds_read_b64 v[140:141], v140
	s_waitcnt lgkmcnt(0)
	v_readfirstlane_b32 s2, v140
	v_readfirstlane_b32 s3, v141
	s_add_i32 s74, s96, 1
	s_lshl_b32 s74, s74, 12
	s_add_u32 s2, s2, s74
	s_addc_u32 s3, s3, 0
	s_nop 4
	global_load_dwordx4 v[208:211], v159, s[2:3]
	global_load_dwordx4 v[212:215], v159, s[2:3] offset:64
	global_load_dwordx4 v[216:219], v159, s[2:3] offset:512
	global_load_dwordx4 v[220:223], v159, s[2:3] offset:576
	s_mov_b32 s74, 0x313000
	v_add_co_u32_e32 v130, vcc, s74, v130
	s_nop 1
	v_addc_co_u32_e32 v131, vcc, 0, v131, vcc
	global_load_dwordx4 v[240:243], v[130:131], off
	global_load_dwordx4 v[244:247], v[130:131], off offset:64
	global_load_dwordx4 v[248:251], v[130:131], off offset:512
	global_load_dwordx4 v[184:187], v[130:131], off offset:576
	v_add_co_u32_e32 v130, vcc, 0x1000, v130
	s_nop 1
	v_addc_co_u32_e32 v131, vcc, 0, v131, vcc
	global_load_dwordx4 v[224:227], v[130:131], off
	global_load_dwordx4 v[228:231], v[130:131], off offset:64
	global_load_dwordx4 v[232:235], v[130:131], off offset:512
	global_load_dwordx4 v[236:239], v[130:131], off offset:576
	global_store_dwordx4 v[146:147], v[124:127], off
	global_store_dwordx4 v[146:147], v[120:123], off offset:64
	global_store_dwordx4 v[146:147], v[116:119], off offset:512
	global_store_dwordx4 v[146:147], v[112:115], off offset:576
	v_lshl_add_u64 v[146:147], v[146:147], 0, s[66:67]
	global_store_dwordx4 v[146:147], v[108:111], off
	global_store_dwordx4 v[146:147], v[104:107], off offset:64
	global_store_dwordx4 v[146:147], v[100:103], off offset:512
	global_store_dwordx4 v[146:147], v[96:99], off offset:576
	v_lshl_add_u64 v[146:147], v[146:147], 0, s[66:67]
	global_store_dwordx4 v[146:147], v[92:95], off
	global_store_dwordx4 v[146:147], v[88:91], off offset:64
	global_store_dwordx4 v[146:147], v[84:87], off offset:512
	global_store_dwordx4 v[146:147], v[80:83], off offset:576
	v_lshl_add_u64 v[146:147], v[146:147], 0, s[66:67]
	global_store_dwordx4 v[146:147], v[76:79], off
	global_store_dwordx4 v[146:147], v[72:75], off offset:64
	global_store_dwordx4 v[146:147], v[68:71], off offset:512
	global_store_dwordx4 v[146:147], v[64:67], off offset:576
	v_lshl_add_u64 v[146:147], v[146:147], 0, s[68:69]
	global_store_dwordx4 v[146:147], v[60:63], off
	global_store_dwordx4 v[146:147], v[56:59], off offset:64
	global_store_dwordx4 v[146:147], v[52:55], off offset:512
	global_store_dwordx4 v[146:147], v[48:51], off offset:576
	v_lshl_add_u64 v[146:147], v[146:147], 0, s[66:67]
	global_store_dwordx4 v[146:147], v[44:47], off
	global_store_dwordx4 v[146:147], v[40:43], off offset:64
	global_store_dwordx4 v[146:147], v[36:39], off offset:512
	global_store_dwordx4 v[146:147], v[32:35], off offset:576
	v_lshl_add_u64 v[146:147], v[146:147], 0, s[66:67]
	global_store_dwordx4 v[146:147], v[28:31], off
	global_store_dwordx4 v[146:147], v[24:27], off offset:64
	global_store_dwordx4 v[146:147], v[20:23], off offset:512
	global_store_dwordx4 v[146:147], v[16:19], off offset:576
	v_lshl_add_u64 v[146:147], v[146:147], 0, s[66:67]
	global_store_dwordx4 v[146:147], v[12:15], off
	global_store_dwordx4 v[146:147], v[8:11], off offset:64
	global_store_dwordx4 v[146:147], v[4:7], off offset:512
	global_store_dwordx4 v[146:147], v[0:3], off offset:576
	s_cmp_eq_u32 s25, 0
	s_cbranch_scc0 .Lfz_dn_nopoll
	s_mov_b64 exec, 1
	v_mov_b32_e32 v140, 0
	v_mov_b32_e32 v141, 1
	global_atomic_add v140, v141, s[98:99]
	s_mov_b32 s65, 0
